# ssd_b C fragments via dwordx4 loads plus permlane32 swap (half the uncoalesced requests); MLA -1e30 init only when a key sub-block is skipped
# speedup vs baseline: 1.0136x; 1.0136x over previous
; DI unsigned pk2(float a, float b) { f32x2_t v = {a, b}; bf16x2_t r = __builtin_convertvector(v, bf16x2_t); return __builtin_bit_cast(unsigned, r); }
; DI float bflo(unsigned u) { return __uint_as_float(u << 16); }
; DI float bfhi(unsigned u) { return __uint_as_float(u & 0xffff0000u); }
; DI float siluf(float v) { return v / (1.f + __expf(-v)); }
; DI f32x16 mfma32(bf16x8 a, bf16x8 b, f32x16 c) { return __builtin_amdgcn_mfma_f32_32x32x16_bf16(a, b, c, 0, 0, 0); }
; DI f32x16 zero16() { f32x16 z; for (int i = 0; i < 16; ++i) z[i] = 0.f; return z; }
; DI void ssd_b_item(PP p, int wg_item) {
;     ...
;             const size_t lrow = r0 + lb * 32 + l31;
;             f32x16 yo = zero16();
;             const bf16_t* cp = p->cc + lrow * 256 + g * 128 + 4 * hh;
; #pragma unroll
;             for (int nb = 0; nb < 4; ++nb)
; #pragma unroll
;                 for (int ks = 0; ks < 2; ++ks) {
;                     const bf16_t* q = cp + nb * 32 + 16 * ks;
;                     yo = mfma32(sp[nb][ks], ld8x2(q, q + 8), yo);
;                 }
;             const float eal = p->ea[lrow * 16 + head];
;             float ss = 0.f;
; #pragma unroll
;             for (int q = 0; q < 4; ++q) {
;                 const int p0 = head * 64 + ph * 32 + 8 * q + 4 * hh;
;                 const u32x2 yd = *(const u32x2*)(p->proj + lrow * PS + PC_X + p0);
;                 bf16_t* zp = p->proj + lrow * PS + PC_Z + p0;
;                 const u32x2 zz = *(const u32x2*)zp;
;                 float y[4], z[4];
;                 y[0] = bflo(yd[0]); y[1] = bfhi(yd[0]); y[2] = bflo(yd[1]); y[3] = bfhi(yd[1]);
;                 z[0] = bflo(zz[0]); z[1] = bfhi(zz[0]); z[2] = bflo(zz[1]); z[3] = bfhi(zz[1]);
; #pragma unroll
;                 for (int e = 0; e < 4; ++e) { y[e] = (y[e] + eal * yo[4 * q + e]) * siluf(z[e]); ss += y[e] * y[e]; }
;                 u32x2 o; o[0] = pk2(y[0], y[1]); o[1] = pk2(y[2], y[3]);
.LBB0_316:
	v_lshl_add_u64 v[190:191], v[196:197], 1, v[174:175]
	v_lshl_add_u64 v[176:177], v[156:157], 0, s[8:9]
	v_add_co_u32_e32 v178, vcc, s33, v176
	s_nop 1
	v_addc_co_u32_e32 v179, vcc, 0, v177, vcc
	s_waitcnt lgkmcnt(0)
	global_load_dword v184, v[170:171], off
	global_load_dwordx4 v[200:203], v[190:191], off
	global_load_dwordx4 v[204:207], v[190:191], off offset:32
	global_load_dwordx4 v[212:215], v[190:191], off offset:64
	global_load_dwordx4 v[216:219], v[190:191], off offset:96
	global_load_dwordx4 v[220:223], v[190:191], off offset:128
	global_load_dwordx4 v[228:231], v[190:191], off offset:160
	global_load_dwordx4 v[232:235], v[190:191], off offset:192
	global_load_dwordx2 v[180:181], v[176:177], off offset:2048
	global_load_dwordx2 v[240:241], v[178:179], off offset:16
	global_load_dwordx2 v[242:243], v[176:177], off offset:2064
	global_load_dwordx2 v[244:245], v[178:179], off offset:32
	global_load_dwordx2 v[250:251], v[176:177], off offset:2080
	global_load_dwordx2 v[236:237], v[178:179], off offset:48
	global_load_dwordx2 v[238:239], v[176:177], off offset:2096
	s_nop 0
	global_load_dwordx2 v[178:179], v[178:179], off
	s_waitcnt vmcnt(14)
	v_permlane32_swap_b32_e32 v200, v202
	v_permlane32_swap_b32_e32 v201, v203
	s_nop 1
	v_mfma_f32_32x32x16_bf16 v[2:17], v[50:53], v[200:203], 0
	s_waitcnt vmcnt(13)
	v_permlane32_swap_b32_e32 v204, v206
	v_permlane32_swap_b32_e32 v205, v207
	s_nop 1
	v_mfma_f32_32x32x16_bf16 v[2:17], v[54:57], v[204:207], v[2:17]
	global_load_dwordx4 v[200:203], v[190:191], off offset:224
	s_waitcnt vmcnt(13)
	v_permlane32_swap_b32_e32 v212, v214
	v_permlane32_swap_b32_e32 v213, v215
	s_nop 1
	v_mfma_f32_32x32x16_bf16 v[2:17], v[58:61], v[212:215], v[2:17]
	s_waitcnt vmcnt(12)
	v_permlane32_swap_b32_e32 v216, v218
	v_permlane32_swap_b32_e32 v217, v219
	s_nop 1
	v_mfma_f32_32x32x16_bf16 v[2:17], v[62:65], v[216:219], v[2:17]
	s_waitcnt vmcnt(11)
	v_permlane32_swap_b32_e32 v220, v222
	v_permlane32_swap_b32_e32 v221, v223
	s_nop 1
	v_mfma_f32_32x32x16_bf16 v[2:17], v[66:69], v[220:223], v[2:17]
	s_waitcnt vmcnt(10)
	v_permlane32_swap_b32_e32 v228, v230
	v_permlane32_swap_b32_e32 v229, v231
	s_nop 1
	v_mfma_f32_32x32x16_bf16 v[2:17], v[70:73], v[228:231], v[2:17]
	s_waitcnt vmcnt(9)
	v_permlane32_swap_b32_e32 v232, v234
	v_permlane32_swap_b32_e32 v233, v235
	s_nop 1
	v_mfma_f32_32x32x16_bf16 v[2:17], v[74:77], v[232:235], v[2:17]
	s_waitcnt vmcnt(0)
	v_permlane32_swap_b32_e32 v200, v202
	v_permlane32_swap_b32_e32 v201, v203
	s_nop 1
	v_mfma_f32_32x32x16_bf16 v[2:17], v[78:81], v[200:203], v[2:17]
	s_nop 7
	s_nop 3
	v_lshlrev_b32_e32 v182, 16, v178
	v_lshlrev_b32_e32 v83, 16, v180
	v_and_b32_e32 v183, 0xffff0000, v178
	v_and_b32_e32 v178, 0xffff0000, v180
	v_mul_f32_e32 v180, 0xbfb8aa3b, v83
	v_exp_f32_e32 v186, v180
	v_mul_f32_e32 v180, 0xbfb8aa3b, v178
	v_exp_f32_e32 v187, v180
	v_pk_fma_f32 v[2:3], v[2:3], v[184:185], v[182:183] op_sel_hi:[1,0,1]
	v_pk_add_f32 v[182:183], v[186:187], 1.0 op_sel_hi:[1,0]
	s_nop 0
	v_div_scale_f32 v180, s[10:11], v183, v183, v178
	v_rcp_f32_e32 v186, v180
	s_nop 0
	v_fma_f32 v187, -v180, v186, 1.0
	v_fmac_f32_e32 v186, v187, v186
	v_div_scale_f32 v187, vcc, v178, v183, v178
	v_mul_f32_e32 v188, v187, v186
	v_fma_f32 v189, -v180, v188, v187
	v_fmac_f32_e32 v188, v189, v186
	v_fma_f32 v180, -v180, v188, v187
	v_div_fmas_f32 v180, v180, v186, v188
	v_div_fixup_f32 v183, v180, v183, v178
	v_div_scale_f32 v178, s[10:11], v182, v182, v83
	v_rcp_f32_e32 v180, v178
	s_nop 0
	v_fma_f32 v186, -v178, v180, 1.0
	v_fmac_f32_e32 v180, v186, v180
	v_div_scale_f32 v186, vcc, v83, v182, v83
	v_mul_f32_e32 v187, v186, v180
	v_fma_f32 v188, -v178, v187, v186
	v_fmac_f32_e32 v187, v188, v180
	v_fma_f32 v178, -v178, v187, v186
	v_div_fmas_f32 v178, v178, v180, v187
	v_div_fixup_f32 v182, v178, v182, v83
	v_lshlrev_b32_e32 v178, 16, v179
	v_and_b32_e32 v179, 0xffff0000, v179
	v_lshlrev_b32_e32 v83, 16, v181
	v_and_b32_e32 v186, 0xffff0000, v181
	v_mul_f32_e32 v180, 0xbfb8aa3b, v83
	v_pk_fma_f32 v[4:5], v[4:5], v[184:185], v[178:179] op_sel_hi:[1,0,1]
	v_mul_f32_e32 v178, 0xbfb8aa3b, v186
	v_exp_f32_e32 v180, v180
	v_exp_f32_e32 v181, v178
	v_pk_mul_f32 v[182:183], v[2:3], v[182:183]
	v_pk_add_f32 v[178:179], v[180:181], 1.0 op_sel_hi:[1,0]
	s_nop 0
	v_div_scale_f32 v180, s[10:11], v179, v179, v186
	v_rcp_f32_e32 v181, v180
	v_pk_mul_f32 v[2:3], v[182:183], v[182:183]
	v_fma_f32 v187, -v180, v181, 1.0
	v_fmac_f32_e32 v181, v187, v181
	v_div_scale_f32 v187, vcc, v186, v179, v186
	v_mul_f32_e32 v188, v187, v181
	v_fma_f32 v189, -v180, v188, v187
	v_fmac_f32_e32 v188, v189, v181
	v_fma_f32 v180, -v180, v188, v187
	v_div_fmas_f32 v180, v180, v181, v188
	v_div_fixup_f32 v179, v180, v179, v186
	v_div_scale_f32 v180, s[10:11], v178, v178, v83
	v_rcp_f32_e32 v181, v180
	v_add_f32_e32 v2, v2, v3
	v_fma_f32 v186, -v180, v181, 1.0
	v_fmac_f32_e32 v181, v186, v181
	v_div_scale_f32 v186, vcc, v83, v178, v83
	v_mul_f32_e32 v187, v186, v181
	v_fma_f32 v188, -v180, v187, v186
	v_fmac_f32_e32 v187, v188, v181
	v_fma_f32 v180, -v180, v187, v186
	v_div_fmas_f32 v180, v180, v181, v187
	v_div_fixup_f32 v178, v180, v178, v83
	v_pk_mul_f32 v[178:179], v[4:5], v[178:179]
	v_cvt_pk_bf16_f32 v180, v182, v183
	v_pk_mul_f32 v[4:5], v[178:179], v[178:179]
	v_cvt_pk_bf16_f32 v181, v178, v179
	global_store_dwordx2 v[176:177], v[180:181], off offset:2048
	v_add_f32_e32 v2, v4, v2
	v_add_f32_e32 v2, v5, v2
	v_lshlrev_b32_e32 v186, 16, v240
	v_lshlrev_b32_e32 v83, 16, v242
	v_and_b32_e32 v187, 0xffff0000, v240
	v_and_b32_e32 v180, 0xffff0000, v242
	v_mul_f32_e32 v182, 0xbfb8aa3b, v83
	v_exp_f32_e32 v188, v182
; DI unsigned pk2(float a, float b) { f32x2_t v = {a, b}; bf16x2_t r = __builtin_convertvector(v, bf16x2_t); return __builtin_bit_cast(unsigned, r); }
; DI float bflo(unsigned u) { return __uint_as_float(u << 16); }
; DI float bfhi(unsigned u) { return __uint_as_float(u & 0xffff0000u); }
; DI float siluf(float v) { return v / (1.f + __expf(-v)); }
; DI void ssd_b_item(PP p, int wg_item) {
;     ...
;             for (int q = 0; q < 4; ++q) {
;                 const int p0 = head * 64 + ph * 32 + 8 * q + 4 * hh;
;                 const u32x2 yd = *(const u32x2*)(p->proj + lrow * PS + PC_X + p0);
;                 bf16_t* zp = p->proj + lrow * PS + PC_Z + p0;
;                 const u32x2 zz = *(const u32x2*)zp;
;                 float y[4], z[4];
;                 y[0] = bflo(yd[0]); y[1] = bfhi(yd[0]); y[2] = bflo(yd[1]); y[3] = bfhi(yd[1]);
;                 z[0] = bflo(zz[0]); z[1] = bfhi(zz[0]); z[2] = bflo(zz[1]); z[3] = bfhi(zz[1]);
; #pragma unroll
;                 for (int e = 0; e < 4; ++e) { y[e] = (y[e] + eal * yo[4 * q + e]) * siluf(z[e]); ss += y[e] * y[e]; }
;                 u32x2 o; o[0] = pk2(y[0], y[1]); o[1] = pk2(y[2], y[3]);
;                 *(u32x2*)zp = o;
;             }
	v_mul_f32_e32 v182, 0xbfb8aa3b, v180
	v_exp_f32_e32 v189, v182
	v_pk_fma_f32 v[6:7], v[6:7], v[184:185], v[186:187] op_sel_hi:[1,0,1]
	v_pk_add_f32 v[186:187], v[188:189], 1.0 op_sel_hi:[1,0]
	s_nop 0
	v_div_scale_f32 v182, s[10:11], v187, v187, v180
	v_rcp_f32_e32 v188, v182
	s_nop 0
	v_fma_f32 v189, -v182, v188, 1.0
	v_fmac_f32_e32 v188, v189, v188
	v_div_scale_f32 v189, vcc, v180, v187, v180
	v_mul_f32_e32 v190, v189, v188
	v_fma_f32 v191, -v182, v190, v189
	v_fmac_f32_e32 v190, v191, v188
	v_fma_f32 v182, -v182, v190, v189
	v_div_fmas_f32 v182, v182, v188, v190
	v_div_fixup_f32 v187, v182, v187, v180
	v_div_scale_f32 v180, s[10:11], v186, v186, v83
	v_rcp_f32_e32 v182, v180
	s_nop 0
	v_fma_f32 v188, -v180, v182, 1.0
	v_fmac_f32_e32 v182, v188, v182
	v_div_scale_f32 v188, vcc, v83, v186, v83
	v_mul_f32_e32 v189, v188, v182
	v_fma_f32 v190, -v180, v189, v188
	v_fmac_f32_e32 v189, v190, v182
	v_fma_f32 v180, -v180, v189, v188
	v_div_fmas_f32 v180, v180, v182, v189
	v_div_fixup_f32 v186, v180, v186, v83
	v_lshlrev_b32_e32 v180, 16, v241
	v_and_b32_e32 v181, 0xffff0000, v241
	v_lshlrev_b32_e32 v83, 16, v243
	v_and_b32_e32 v188, 0xffff0000, v243
	v_mul_f32_e32 v182, 0xbfb8aa3b, v83
	v_pk_fma_f32 v[8:9], v[8:9], v[184:185], v[180:181] op_sel_hi:[1,0,1]
	v_mul_f32_e32 v180, 0xbfb8aa3b, v188
	v_exp_f32_e32 v182, v182
	v_exp_f32_e32 v183, v180
	v_pk_mul_f32 v[186:187], v[6:7], v[186:187]
	v_pk_add_f32 v[180:181], v[182:183], 1.0 op_sel_hi:[1,0]
	s_nop 0
	v_div_scale_f32 v182, s[10:11], v181, v181, v188
	v_rcp_f32_e32 v183, v182
	v_pk_mul_f32 v[6:7], v[186:187], v[186:187]
	v_fma_f32 v189, -v182, v183, 1.0
	v_fmac_f32_e32 v183, v189, v183
	v_div_scale_f32 v189, vcc, v188, v181, v188
	v_mul_f32_e32 v190, v189, v183
	v_fma_f32 v191, -v182, v190, v189
	v_fmac_f32_e32 v190, v191, v183
	v_fma_f32 v182, -v182, v190, v189
	v_div_fmas_f32 v182, v182, v183, v190
	v_div_fixup_f32 v181, v182, v181, v188
	v_div_scale_f32 v182, s[10:11], v180, v180, v83
	v_rcp_f32_e32 v183, v182
	v_add_f32_e32 v2, v2, v6
	v_add_f32_e32 v2, v7, v2
	v_fma_f32 v188, -v182, v183, 1.0
	v_fmac_f32_e32 v183, v188, v183
	v_div_scale_f32 v188, vcc, v83, v180, v83
	v_mul_f32_e32 v189, v188, v183
	v_fma_f32 v190, -v182, v189, v188
	v_fmac_f32_e32 v189, v190, v183
	v_fma_f32 v182, -v182, v189, v188
	v_div_fmas_f32 v182, v182, v183, v189
	v_div_fixup_f32 v180, v182, v180, v83
	v_pk_mul_f32 v[180:181], v[8:9], v[180:181]
	v_cvt_pk_bf16_f32 v182, v186, v187
	v_cvt_pk_bf16_f32 v183, v180, v181
	global_store_dwordx2 v[176:177], v[182:183], off offset:2064
	v_pk_mul_f32 v[8:9], v[180:181], v[180:181]
	v_add_f32_e32 v2, v8, v2
	v_add_f32_e32 v2, v9, v2
	v_lshlrev_b32_e32 v186, 16, v244
	v_and_b32_e32 v187, 0xffff0000, v244
	v_lshlrev_b32_e32 v83, 16, v250
	v_and_b32_e32 v180, 0xffff0000, v250
	v_mul_f32_e32 v188, 0xbfb8aa3b, v83
	v_pk_fma_f32 v[10:11], v[10:11], v[184:185], v[186:187] op_sel_hi:[1,0,1]
	v_mul_f32_e32 v186, 0xbfb8aa3b, v180
	v_exp_f32_e32 v190, v188
	v_exp_f32_e32 v191, v186
	s_nop 0
	v_pk_add_f32 v[186:187], v[190:191], 1.0 op_sel_hi:[1,0]
	s_nop 0
	v_div_scale_f32 v188, s[10:11], v187, v187, v180
	v_rcp_f32_e32 v190, v188
	s_nop 0
	v_fma_f32 v191, -v188, v190, 1.0
	v_fmac_f32_e32 v190, v191, v190
	v_div_scale_f32 v191, vcc, v180, v187, v180
	v_mul_f32_e32 v194, v191, v190
	v_fma_f32 v195, -v188, v194, v191
	v_fmac_f32_e32 v194, v195, v190
	v_fma_f32 v188, -v188, v194, v191
	v_div_fmas_f32 v188, v188, v190, v194
	v_div_fixup_f32 v187, v188, v187, v180
	v_div_scale_f32 v180, s[10:11], v186, v186, v83
	v_rcp_f32_e32 v188, v180
	s_nop 0
	v_fma_f32 v190, -v180, v188, 1.0
	v_fmac_f32_e32 v188, v190, v188
	v_div_scale_f32 v190, vcc, v83, v186, v83
	v_mul_f32_e32 v191, v190, v188
	v_fma_f32 v194, -v180, v191, v190
	v_fmac_f32_e32 v191, v194, v188
	v_fma_f32 v180, -v180, v191, v190
	v_div_fmas_f32 v180, v180, v188, v191
	v_div_fixup_f32 v186, v180, v186, v83
	v_pk_mul_f32 v[190:191], v[10:11], v[186:187]
	v_lshlrev_b32_e32 v10, 16, v245
	v_and_b32_e32 v11, 0xffff0000, v245
	v_lshlrev_b32_e32 v83, 16, v251
	v_and_b32_e32 v188, 0xffff0000, v251
	v_mul_f32_e32 v180, 0xbfb8aa3b, v83
	v_pk_fma_f32 v[10:11], v[12:13], v[184:185], v[10:11] op_sel_hi:[1,0,1]
	v_mul_f32_e32 v12, 0xbfb8aa3b, v188
	v_exp_f32_e32 v180, v180
	v_exp_f32_e32 v181, v12
	v_pk_mul_f32 v[186:187], v[190:191], v[190:191]
; DI unsigned pk2(float a, float b) { f32x2_t v = {a, b}; bf16x2_t r = __builtin_convertvector(v, bf16x2_t); return __builtin_bit_cast(unsigned, r); }
; DI float bflo(unsigned u) { return __uint_as_float(u << 16); }
; DI float bfhi(unsigned u) { return __uint_as_float(u & 0xffff0000u); }
; DI float siluf(float v) { return v / (1.f + __expf(-v)); }
; DI void ssd_b_item(PP p, int wg_item) {
;     ...
;             for (int q = 0; q < 4; ++q) {
;                 const int p0 = head * 64 + ph * 32 + 8 * q + 4 * hh;
;                 const u32x2 yd = *(const u32x2*)(p->proj + lrow * PS + PC_X + p0);
;                 bf16_t* zp = p->proj + lrow * PS + PC_Z + p0;
;                 const u32x2 zz = *(const u32x2*)zp;
;                 float y[4], z[4];
;                 y[0] = bflo(yd[0]); y[1] = bfhi(yd[0]); y[2] = bflo(yd[1]); y[3] = bfhi(yd[1]);
;                 z[0] = bflo(zz[0]); z[1] = bfhi(zz[0]); z[2] = bflo(zz[1]); z[3] = bfhi(zz[1]);
; #pragma unroll
;                 for (int e = 0; e < 4; ++e) { y[e] = (y[e] + eal * yo[4 * q + e]) * siluf(z[e]); ss += y[e] * y[e]; }
;                 u32x2 o; o[0] = pk2(y[0], y[1]); o[1] = pk2(y[2], y[3]);
;                 *(u32x2*)zp = o;
;             }
;             ss += __shfl_xor(ss, 32);
;             if (hh == 0) p->ssqm[lrow * 32 + head * 2 + ph] = ss;
	v_pk_add_f32 v[12:13], v[180:181], 1.0 op_sel_hi:[1,0]
	s_nop 0
	v_div_scale_f32 v180, s[10:11], v13, v13, v188
	v_rcp_f32_e32 v181, v180
	v_add_f32_e32 v2, v186, v2
	v_add_f32_e32 v2, v187, v2
	v_fma_f32 v189, -v180, v181, 1.0
	v_fmac_f32_e32 v181, v189, v181
	v_div_scale_f32 v189, vcc, v188, v13, v188
	v_mul_f32_e32 v194, v189, v181
	v_fma_f32 v195, -v180, v194, v189
	v_fmac_f32_e32 v194, v195, v181
	v_fma_f32 v180, -v180, v194, v189
	v_div_fmas_f32 v180, v180, v181, v194
	v_div_fixup_f32 v13, v180, v13, v188
	v_div_scale_f32 v180, s[10:11], v12, v12, v83
	v_rcp_f32_e32 v181, v180
	s_nop 0
	v_fma_f32 v188, -v180, v181, 1.0
	v_fmac_f32_e32 v181, v188, v181
	v_div_scale_f32 v188, vcc, v83, v12, v83
	v_mul_f32_e32 v189, v188, v181
	v_fma_f32 v194, -v180, v189, v188
	v_fmac_f32_e32 v189, v194, v181
	v_fma_f32 v180, -v180, v189, v188
	v_div_fmas_f32 v180, v180, v181, v189
	v_div_fixup_f32 v12, v180, v12, v83
	v_pk_mul_f32 v[12:13], v[10:11], v[12:13]
	v_cvt_pk_bf16_f32 v180, v190, v191
	v_cvt_pk_bf16_f32 v181, v12, v13
	global_store_dwordx2 v[176:177], v[180:181], off offset:2080
	v_pk_mul_f32 v[10:11], v[12:13], v[12:13]
	v_add_f32_e32 v2, v10, v2
	v_add_f32_e32 v2, v11, v2
	v_lshlrev_b32_e32 v188, 16, v236
	v_and_b32_e32 v189, 0xffff0000, v236
	v_lshlrev_b32_e32 v12, 16, v238
	v_and_b32_e32 v83, 0xffff0000, v238
	v_mul_f32_e32 v190, 0xbfb8aa3b, v12
	v_pk_fma_f32 v[14:15], v[14:15], v[184:185], v[188:189] op_sel_hi:[1,0,1]
	v_mul_f32_e32 v188, 0xbfb8aa3b, v83
	v_exp_f32_e32 v194, v190
	v_exp_f32_e32 v195, v188
	s_nop 0
	v_pk_add_f32 v[188:189], v[194:195], 1.0 op_sel_hi:[1,0]
	s_nop 0
	v_div_scale_f32 v190, s[10:11], v189, v189, v83
	v_rcp_f32_e32 v194, v190
	s_nop 0
	v_fma_f32 v195, -v190, v194, 1.0
	v_fmac_f32_e32 v194, v195, v194
	v_div_scale_f32 v195, vcc, v83, v189, v83
	v_mul_f32_e32 v198, v195, v194
	v_fma_f32 v199, -v190, v198, v195
	v_fmac_f32_e32 v198, v199, v194
	v_fma_f32 v190, -v190, v198, v195
	v_div_fmas_f32 v190, v190, v194, v198
	v_div_fixup_f32 v189, v190, v189, v83
	v_div_scale_f32 v83, s[10:11], v188, v188, v12
	v_rcp_f32_e32 v190, v83
	s_nop 0
	v_fma_f32 v194, -v83, v190, 1.0
	v_fmac_f32_e32 v190, v194, v190
	v_div_scale_f32 v194, vcc, v12, v188, v12
	v_mul_f32_e32 v195, v194, v190
	v_fma_f32 v198, -v83, v195, v194
	v_fmac_f32_e32 v195, v198, v190
	v_fma_f32 v83, -v83, v195, v194
	v_div_fmas_f32 v83, v83, v190, v195
	v_div_fixup_f32 v188, v83, v188, v12
	v_lshlrev_b32_e32 v12, 16, v237
	v_and_b32_e32 v13, 0xffff0000, v237
	v_lshlrev_b32_e32 v83, 16, v239
	v_and_b32_e32 v194, 0xffff0000, v239
	v_mul_f32_e32 v190, 0xbfb8aa3b, v83
	v_pk_fma_f32 v[12:13], v[16:17], v[184:185], v[12:13] op_sel_hi:[1,0,1]
	v_mul_f32_e32 v16, 0xbfb8aa3b, v194
	v_exp_f32_e32 v190, v190
	v_exp_f32_e32 v191, v16
	v_pk_mul_f32 v[14:15], v[14:15], v[188:189]
	v_pk_add_f32 v[16:17], v[190:191], 1.0 op_sel_hi:[1,0]
	s_nop 0
	v_div_scale_f32 v184, s[10:11], v17, v17, v194
	v_rcp_f32_e32 v190, v184
	v_pk_mul_f32 v[188:189], v[14:15], v[14:15]
	v_cvt_pk_bf16_f32 v4, v14, v15
	v_add_f32_e32 v2, v188, v2
	v_fma_f32 v191, -v184, v190, 1.0
	v_fmac_f32_e32 v190, v191, v190
	v_div_scale_f32 v191, vcc, v194, v17, v194
	v_mul_f32_e32 v195, v191, v190
	v_fma_f32 v198, -v184, v195, v191
	v_fmac_f32_e32 v195, v198, v190
	v_fma_f32 v184, -v184, v195, v191
	v_div_fmas_f32 v184, v184, v190, v195
	v_div_fixup_f32 v17, v184, v17, v194
	v_div_scale_f32 v184, s[10:11], v16, v16, v83
	v_rcp_f32_e32 v190, v184
	v_add_f32_e32 v2, v189, v2
	v_fma_f32 v191, -v184, v190, 1.0
	v_fmac_f32_e32 v190, v191, v190
	v_div_scale_f32 v191, vcc, v83, v16, v83
	v_mul_f32_e32 v194, v191, v190
	v_fma_f32 v195, -v184, v194, v191
	v_fmac_f32_e32 v194, v195, v190
	v_fma_f32 v184, -v184, v194, v191
	v_div_fmas_f32 v184, v184, v190, v194
	v_div_fixup_f32 v16, v184, v16, v83
	v_pk_mul_f32 v[12:13], v[12:13], v[16:17]
	s_nop 0
	v_pk_mul_f32 v[16:17], v[12:13], v[12:13]
	v_cvt_pk_bf16_f32 v5, v12, v13
	v_add_f32_e32 v2, v16, v2
	v_add_f32_e32 v2, v17, v2
	ds_bpermute_b32 v3, v193, v2
	global_store_dwordx2 v[176:177], v[4:5], off offset:2096
	s_and_saveexec_b64 s[10:11], s[6:7]
	s_cbranch_execz .LBB0_315
	s_load_dwordx2 s[12:13], s[82:83], 0x120
	s_waitcnt lgkmcnt(0)
	v_add_f32_e32 v4, v2, v3
	v_lshl_add_u64 v[2:3], s[12:13], 0, v[154:155]
	v_lshl_add_u64 v[2:3], v[2:3], 0, s[4:5]
	global_store_dword v[2:3], v4, off
	s_branch .LBB0_315
